# norm_mod(0): modulation prologue runs before the six rows' x loads are issued, so each row starts when its own data lands (counted waits) instead of behind the prologue's drain
# speedup vs baseline: 1.0075x; 1.0075x over previous
.LBB0_101:
	s_waitcnt vmcnt(4)
	v_add_u32_e32 v145, 0xffffe000, v144
	v_ashrrev_i32_e32 v145, 10, v145
	v_add_u32_e32 v145, 1, v145
	v_cmp_lt_i32_e32 vcc, s13, v144
	s_nop 1
	v_cndmask_b32_e32 v145, 0, v145, vcc
	v_cmp_ne_u32_e32 vcc, v145, v185
	s_and_saveexec_b64 s[6:7], vcc
	s_cbranch_execz .Lnm0_early_skip
	v_mad_i64_i32 v[172:173], s[8:9], v145, s3, v[160:161]
	global_load_dwordx4 v[16:19], v[150:151], off
	global_load_dwordx4 v[20:23], v[152:153], off
	v_add_co_u32_e32 v222, vcc, 0x1410000, v172
	s_nop 1
	v_addc_co_u32_e32 v223, vcc, 0, v173, vcc
	global_load_dwordx4 v[186:189], v[222:223], off
	v_add_co_u32_e32 v222, vcc, 0x1000, v222
	s_nop 1
	v_addc_co_u32_e32 v223, vcc, 0, v223, vcc
	global_load_dwordx4 v[190:193], v[222:223], off
	v_add_co_u32_e32 v222, vcc, 0x1d000, v222
	s_nop 1
	v_addc_co_u32_e32 v223, vcc, 0, v223, vcc
	global_load_dwordx4 v[194:197], v[222:223], off
	v_add_co_u32_e32 v222, vcc, 0x1000, v222
	s_nop 1
	v_addc_co_u32_e32 v223, vcc, 0, v223, vcc
	global_load_dwordx4 v[198:201], v[222:223], off
	v_add_co_u32_e32 v222, vcc, 0x1d000, v222
	s_nop 1
	v_addc_co_u32_e32 v223, vcc, 0, v223, vcc
	global_load_dwordx4 v[202:205], v[222:223], off
	v_add_co_u32_e32 v222, vcc, 0x1000, v222
	s_nop 1
	v_addc_co_u32_e32 v223, vcc, 0, v223, vcc
	global_load_dwordx4 v[206:209], v[222:223], off
	v_add_co_u32_e32 v222, vcc, 0x1d000, v222
	s_nop 1
	v_addc_co_u32_e32 v223, vcc, 0, v223, vcc
	global_load_dwordx4 v[210:213], v[222:223], off
	v_add_co_u32_e32 v222, vcc, 0x1000, v222
	s_nop 1
	v_addc_co_u32_e32 v223, vcc, 0, v223, vcc
	global_load_dwordx4 v[214:217], v[222:223], off
	v_add_co_u32_e32 v222, vcc, 0x1d000, v222
	s_nop 1
	v_addc_co_u32_e32 v223, vcc, 0, v223, vcc
	global_load_dwordx4 v[218:221], v[222:223], off
	v_add_co_u32_e32 v222, vcc, 0x1000, v222
	s_nop 1
	v_addc_co_u32_e32 v223, vcc, 0, v223, vcc
	global_load_dwordx4 v[226:229], v[222:223], off
	v_add_co_u32_e32 v222, vcc, 0x1d000, v222
	s_nop 1
	v_addc_co_u32_e32 v223, vcc, 0, v223, vcc
	global_load_dwordx4 v[230:233], v[222:223], off
	v_add_co_u32_e32 v222, vcc, 0x1000, v222
	s_nop 1
	v_addc_co_u32_e32 v223, vcc, 0, v223, vcc
	global_load_dwordx4 v[234:237], v[222:223], off
	v_add_co_u32_e32 v222, vcc, 0x1d000, v222
	s_nop 1
	v_addc_co_u32_e32 v223, vcc, 0, v223, vcc
	global_load_dwordx4 v[238:241], v[222:223], off
	v_add_co_u32_e32 v222, vcc, 0x1000, v222
	s_nop 1
	v_addc_co_u32_e32 v223, vcc, 0, v223, vcc
	global_load_dwordx4 v[242:245], v[222:223], off
	v_add_co_u32_e32 v222, vcc, 0x1d000, v222
	s_nop 1
	v_addc_co_u32_e32 v223, vcc, 0, v223, vcc
	global_load_dwordx4 v[246:249], v[222:223], off
	v_add_co_u32_e32 v222, vcc, 0x1000, v222
	s_nop 1
	v_addc_co_u32_e32 v223, vcc, 0, v223, vcc
	global_load_dwordx4 v[250:253], v[222:223], off
	s_waitcnt vmcnt(15)
	v_pk_add_f32 v[18:19], v[18:19], v[188:189]
	v_pk_add_f32 v[16:17], v[16:17], v[186:187]
	global_load_dwordx4 v[40:43], v[150:151], off offset:1024
	global_load_dwordx4 v[44:47], v[154:155], off
	v_add_co_u32_e32 v222, vcc, 0x1410000, v172
	s_nop 1
	v_addc_co_u32_e32 v223, vcc, 0, v173, vcc
	global_load_dwordx4 v[186:189], v[222:223], off offset:1024
	s_waitcnt vmcnt(17)
	v_pk_add_f32 v[22:23], v[22:23], v[192:193]
	v_pk_add_f32 v[20:21], v[20:21], v[190:191]
	v_add_co_u32_e32 v222, vcc, 0x1000, v222
	s_nop 1
	v_addc_co_u32_e32 v223, vcc, 0, v223, vcc
	global_load_dwordx4 v[190:193], v[222:223], off offset:1024
	s_waitcnt vmcnt(17)
	v_pk_add_f32 v[18:19], v[18:19], v[196:197]
	v_pk_add_f32 v[16:17], v[16:17], v[194:195]
	v_add_co_u32_e32 v222, vcc, 0x1d000, v222
	s_nop 1
	v_addc_co_u32_e32 v223, vcc, 0, v223, vcc
	global_load_dwordx4 v[194:197], v[222:223], off offset:1024
	s_waitcnt vmcnt(17)
	v_pk_add_f32 v[22:23], v[22:23], v[200:201]
	v_pk_add_f32 v[20:21], v[20:21], v[198:199]
	v_add_co_u32_e32 v222, vcc, 0x1000, v222
	s_nop 1
	v_addc_co_u32_e32 v223, vcc, 0, v223, vcc
	global_load_dwordx4 v[198:201], v[222:223], off offset:1024
	s_waitcnt vmcnt(17)
	v_pk_add_f32 v[18:19], v[18:19], v[204:205]
	v_pk_add_f32 v[16:17], v[16:17], v[202:203]
	v_add_co_u32_e32 v222, vcc, 0x1d000, v222
	s_nop 1
	v_addc_co_u32_e32 v223, vcc, 0, v223, vcc
	global_load_dwordx4 v[202:205], v[222:223], off offset:1024
	s_waitcnt vmcnt(17)
	v_pk_add_f32 v[22:23], v[22:23], v[208:209]
	v_pk_add_f32 v[20:21], v[20:21], v[206:207]
	v_add_co_u32_e32 v222, vcc, 0x1000, v222
	s_nop 1
	v_addc_co_u32_e32 v223, vcc, 0, v223, vcc
	global_load_dwordx4 v[206:209], v[222:223], off offset:1024
	s_waitcnt vmcnt(17)
	v_pk_add_f32 v[18:19], v[18:19], v[212:213]
	v_pk_add_f32 v[16:17], v[16:17], v[210:211]
	v_add_co_u32_e32 v222, vcc, 0x1d000, v222
	s_nop 1
	v_addc_co_u32_e32 v223, vcc, 0, v223, vcc
	global_load_dwordx4 v[210:213], v[222:223], off offset:1024
	s_waitcnt vmcnt(17)
	v_pk_add_f32 v[22:23], v[22:23], v[216:217]
	v_pk_add_f32 v[20:21], v[20:21], v[214:215]
	v_add_co_u32_e32 v222, vcc, 0x1000, v222
	s_nop 1
	v_addc_co_u32_e32 v223, vcc, 0, v223, vcc
	global_load_dwordx4 v[214:217], v[222:223], off offset:1024
	s_waitcnt vmcnt(17)
	v_pk_add_f32 v[18:19], v[18:19], v[220:221]
	v_pk_add_f32 v[16:17], v[16:17], v[218:219]
	v_add_co_u32_e32 v222, vcc, 0x1d000, v222
	s_nop 1
	v_addc_co_u32_e32 v223, vcc, 0, v223, vcc
	global_load_dwordx4 v[218:221], v[222:223], off offset:1024
	s_waitcnt vmcnt(17)
	v_pk_add_f32 v[22:23], v[22:23], v[228:229]
	v_pk_add_f32 v[20:21], v[20:21], v[226:227]
	v_add_co_u32_e32 v222, vcc, 0x1000, v222
	s_nop 1
	v_addc_co_u32_e32 v223, vcc, 0, v223, vcc
	global_load_dwordx4 v[226:229], v[222:223], off offset:1024
	s_waitcnt vmcnt(17)
	v_pk_add_f32 v[18:19], v[18:19], v[232:233]
	v_pk_add_f32 v[16:17], v[16:17], v[230:231]
	v_add_co_u32_e32 v222, vcc, 0x1d000, v222
	s_nop 1
	v_addc_co_u32_e32 v223, vcc, 0, v223, vcc
	global_load_dwordx4 v[230:233], v[222:223], off offset:1024
	s_waitcnt vmcnt(17)
	v_pk_add_f32 v[22:23], v[22:23], v[236:237]
	v_pk_add_f32 v[20:21], v[20:21], v[234:235]
	v_add_co_u32_e32 v222, vcc, 0x1000, v222
	s_nop 1
	v_addc_co_u32_e32 v223, vcc, 0, v223, vcc
	global_load_dwordx4 v[234:237], v[222:223], off offset:1024
	s_waitcnt vmcnt(17)
	v_pk_add_f32 v[18:19], v[18:19], v[240:241]
	v_pk_add_f32 v[16:17], v[16:17], v[238:239]
	v_add_co_u32_e32 v222, vcc, 0x1d000, v222
	s_nop 1
	v_addc_co_u32_e32 v223, vcc, 0, v223, vcc
	global_load_dwordx4 v[238:241], v[222:223], off offset:1024
	s_waitcnt vmcnt(17)
	v_pk_add_f32 v[22:23], v[22:23], v[244:245]
	v_pk_add_f32 v[20:21], v[20:21], v[242:243]
	v_add_co_u32_e32 v222, vcc, 0x1000, v222
	s_nop 1
	v_addc_co_u32_e32 v223, vcc, 0, v223, vcc
	global_load_dwordx4 v[242:245], v[222:223], off offset:1024
	s_waitcnt vmcnt(17)
	v_pk_add_f32 v[18:19], v[18:19], v[248:249]
	v_pk_add_f32 v[16:17], v[16:17], v[246:247]
	v_add_co_u32_e32 v222, vcc, 0x1d000, v222
	s_nop 1
	v_addc_co_u32_e32 v223, vcc, 0, v223, vcc
	global_load_dwordx4 v[246:249], v[222:223], off offset:1024
	s_waitcnt vmcnt(17)
	v_pk_add_f32 v[22:23], v[22:23], v[252:253]
	v_pk_add_f32 v[20:21], v[20:21], v[250:251]
	v_add_co_u32_e32 v222, vcc, 0x1000, v222
	s_nop 1
	v_addc_co_u32_e32 v223, vcc, 0, v223, vcc
	global_load_dwordx4 v[250:253], v[222:223], off offset:1024
	s_waitcnt vmcnt(15)
	v_pk_add_f32 v[42:43], v[42:43], v[188:189]
	v_pk_add_f32 v[40:41], v[40:41], v[186:187]
	global_load_dwordx4 v[64:67], v[150:151], off offset:2048
	global_load_dwordx4 v[68:71], v[156:157], off
	v_add_co_u32_e32 v222, vcc, 0x1410000, v172
	s_nop 1
	v_addc_co_u32_e32 v223, vcc, 0, v173, vcc
	global_load_dwordx4 v[186:189], v[222:223], off offset:2048
	s_waitcnt vmcnt(17)
	v_pk_add_f32 v[46:47], v[46:47], v[192:193]
	v_pk_add_f32 v[44:45], v[44:45], v[190:191]
	v_add_co_u32_e32 v222, vcc, 0x1000, v222
	s_nop 1
	v_addc_co_u32_e32 v223, vcc, 0, v223, vcc
	global_load_dwordx4 v[190:193], v[222:223], off offset:2048
	s_waitcnt vmcnt(17)
	v_pk_add_f32 v[42:43], v[42:43], v[196:197]
	v_pk_add_f32 v[40:41], v[40:41], v[194:195]
	v_add_co_u32_e32 v222, vcc, 0x1d000, v222
	s_nop 1
	v_addc_co_u32_e32 v223, vcc, 0, v223, vcc
	global_load_dwordx4 v[194:197], v[222:223], off offset:2048
	s_waitcnt vmcnt(17)
	v_pk_add_f32 v[46:47], v[46:47], v[200:201]
	v_pk_add_f32 v[44:45], v[44:45], v[198:199]
	v_add_co_u32_e32 v222, vcc, 0x1000, v222
	s_nop 1
	v_addc_co_u32_e32 v223, vcc, 0, v223, vcc
	global_load_dwordx4 v[198:201], v[222:223], off offset:2048
	s_waitcnt vmcnt(17)
	v_pk_add_f32 v[42:43], v[42:43], v[204:205]
	v_pk_add_f32 v[40:41], v[40:41], v[202:203]
	v_add_co_u32_e32 v222, vcc, 0x1d000, v222
	s_nop 1
	v_addc_co_u32_e32 v223, vcc, 0, v223, vcc
	global_load_dwordx4 v[202:205], v[222:223], off offset:2048
	s_waitcnt vmcnt(17)
	v_pk_add_f32 v[46:47], v[46:47], v[208:209]
	v_pk_add_f32 v[44:45], v[44:45], v[206:207]
	v_add_co_u32_e32 v222, vcc, 0x1000, v222
	s_nop 1
	v_addc_co_u32_e32 v223, vcc, 0, v223, vcc
	global_load_dwordx4 v[206:209], v[222:223], off offset:2048
	s_waitcnt vmcnt(17)
	v_pk_add_f32 v[42:43], v[42:43], v[212:213]
	v_pk_add_f32 v[40:41], v[40:41], v[210:211]
	v_add_co_u32_e32 v222, vcc, 0x1d000, v222
	s_nop 1
	v_addc_co_u32_e32 v223, vcc, 0, v223, vcc
	global_load_dwordx4 v[210:213], v[222:223], off offset:2048
	s_waitcnt vmcnt(17)
	v_pk_add_f32 v[46:47], v[46:47], v[216:217]
	v_pk_add_f32 v[44:45], v[44:45], v[214:215]
	v_add_co_u32_e32 v222, vcc, 0x1000, v222
	s_nop 1
	v_addc_co_u32_e32 v223, vcc, 0, v223, vcc
	global_load_dwordx4 v[214:217], v[222:223], off offset:2048
	s_waitcnt vmcnt(17)
	v_pk_add_f32 v[42:43], v[42:43], v[220:221]
	v_pk_add_f32 v[40:41], v[40:41], v[218:219]
	v_add_co_u32_e32 v222, vcc, 0x1d000, v222
	s_nop 1
	v_addc_co_u32_e32 v223, vcc, 0, v223, vcc
	global_load_dwordx4 v[218:221], v[222:223], off offset:2048
	s_waitcnt vmcnt(17)
	v_pk_add_f32 v[46:47], v[46:47], v[228:229]
	v_pk_add_f32 v[44:45], v[44:45], v[226:227]
	v_add_co_u32_e32 v222, vcc, 0x1000, v222
	s_nop 1
	v_addc_co_u32_e32 v223, vcc, 0, v223, vcc
	global_load_dwordx4 v[226:229], v[222:223], off offset:2048
	s_waitcnt vmcnt(17)
	v_pk_add_f32 v[42:43], v[42:43], v[232:233]
	v_pk_add_f32 v[40:41], v[40:41], v[230:231]
	v_add_co_u32_e32 v222, vcc, 0x1d000, v222
	s_nop 1
	v_addc_co_u32_e32 v223, vcc, 0, v223, vcc
	global_load_dwordx4 v[230:233], v[222:223], off offset:2048
	s_waitcnt vmcnt(17)
	v_pk_add_f32 v[46:47], v[46:47], v[236:237]
	v_pk_add_f32 v[44:45], v[44:45], v[234:235]
	v_add_co_u32_e32 v222, vcc, 0x1000, v222
	s_nop 1
	v_addc_co_u32_e32 v223, vcc, 0, v223, vcc
	global_load_dwordx4 v[234:237], v[222:223], off offset:2048
	s_waitcnt vmcnt(17)
	v_pk_add_f32 v[42:43], v[42:43], v[240:241]
	v_pk_add_f32 v[40:41], v[40:41], v[238:239]
	v_add_co_u32_e32 v222, vcc, 0x1d000, v222
	s_nop 1
	v_addc_co_u32_e32 v223, vcc, 0, v223, vcc
	global_load_dwordx4 v[238:241], v[222:223], off offset:2048
	s_waitcnt vmcnt(17)
	v_pk_add_f32 v[46:47], v[46:47], v[244:245]
	v_pk_add_f32 v[44:45], v[44:45], v[242:243]
	v_add_co_u32_e32 v222, vcc, 0x1000, v222
	s_nop 1
	v_addc_co_u32_e32 v223, vcc, 0, v223, vcc
	global_load_dwordx4 v[242:245], v[222:223], off offset:2048
	s_waitcnt vmcnt(17)
	v_pk_add_f32 v[42:43], v[42:43], v[248:249]
	v_pk_add_f32 v[40:41], v[40:41], v[246:247]
	v_add_co_u32_e32 v222, vcc, 0x1d000, v222
	s_nop 1
	v_addc_co_u32_e32 v223, vcc, 0, v223, vcc
	global_load_dwordx4 v[246:249], v[222:223], off offset:2048
	s_waitcnt vmcnt(17)
	v_pk_add_f32 v[46:47], v[46:47], v[252:253]
	v_pk_add_f32 v[44:45], v[44:45], v[250:251]
	v_add_co_u32_e32 v222, vcc, 0x1000, v222
	s_nop 1
	v_addc_co_u32_e32 v223, vcc, 0, v223, vcc
	global_load_dwordx4 v[250:253], v[222:223], off offset:2048
	s_waitcnt vmcnt(15)
	v_pk_add_f32 v[66:67], v[66:67], v[188:189]
	v_pk_add_f32 v[64:65], v[64:65], v[186:187]
	global_load_dwordx4 v[88:91], v[150:151], off offset:3072
	global_load_dwordx4 v[92:95], v[158:159], off
	v_add_co_u32_e32 v222, vcc, 0x1410000, v172
	s_nop 1
	v_addc_co_u32_e32 v223, vcc, 0, v173, vcc
	global_load_dwordx4 v[186:189], v[222:223], off offset:3072
	s_waitcnt vmcnt(17)
	v_pk_add_f32 v[70:71], v[70:71], v[192:193]
	v_pk_add_f32 v[68:69], v[68:69], v[190:191]
	v_add_co_u32_e32 v222, vcc, 0x1000, v222
	s_nop 1
	v_addc_co_u32_e32 v223, vcc, 0, v223, vcc
	global_load_dwordx4 v[190:193], v[222:223], off offset:3072
	s_waitcnt vmcnt(17)
	v_pk_add_f32 v[66:67], v[66:67], v[196:197]
	v_pk_add_f32 v[64:65], v[64:65], v[194:195]
	v_add_co_u32_e32 v222, vcc, 0x1d000, v222
	s_nop 1
	v_addc_co_u32_e32 v223, vcc, 0, v223, vcc
	global_load_dwordx4 v[194:197], v[222:223], off offset:3072
	s_waitcnt vmcnt(17)
	v_pk_add_f32 v[70:71], v[70:71], v[200:201]
	v_pk_add_f32 v[68:69], v[68:69], v[198:199]
	v_add_co_u32_e32 v222, vcc, 0x1000, v222
	s_nop 1
	v_addc_co_u32_e32 v223, vcc, 0, v223, vcc
	global_load_dwordx4 v[198:201], v[222:223], off offset:3072
	s_waitcnt vmcnt(17)
	v_pk_add_f32 v[66:67], v[66:67], v[204:205]
	v_pk_add_f32 v[64:65], v[64:65], v[202:203]
	v_add_co_u32_e32 v222, vcc, 0x1d000, v222
	s_nop 1
	v_addc_co_u32_e32 v223, vcc, 0, v223, vcc
	global_load_dwordx4 v[202:205], v[222:223], off offset:3072
	s_waitcnt vmcnt(17)
	v_pk_add_f32 v[70:71], v[70:71], v[208:209]
	v_pk_add_f32 v[68:69], v[68:69], v[206:207]
	v_add_co_u32_e32 v222, vcc, 0x1000, v222
	s_nop 1
	v_addc_co_u32_e32 v223, vcc, 0, v223, vcc
	global_load_dwordx4 v[206:209], v[222:223], off offset:3072
	s_waitcnt vmcnt(17)
	v_pk_add_f32 v[66:67], v[66:67], v[212:213]
	v_pk_add_f32 v[64:65], v[64:65], v[210:211]
	v_add_co_u32_e32 v222, vcc, 0x1d000, v222
	s_nop 1
	v_addc_co_u32_e32 v223, vcc, 0, v223, vcc
	global_load_dwordx4 v[210:213], v[222:223], off offset:3072
	s_waitcnt vmcnt(17)
	v_pk_add_f32 v[70:71], v[70:71], v[216:217]
	v_pk_add_f32 v[68:69], v[68:69], v[214:215]
	v_add_co_u32_e32 v222, vcc, 0x1000, v222
	s_nop 1
	v_addc_co_u32_e32 v223, vcc, 0, v223, vcc
	global_load_dwordx4 v[214:217], v[222:223], off offset:3072
	s_waitcnt vmcnt(17)
	v_pk_add_f32 v[66:67], v[66:67], v[220:221]
	v_pk_add_f32 v[64:65], v[64:65], v[218:219]
	v_add_co_u32_e32 v222, vcc, 0x1d000, v222
	s_nop 1
	v_addc_co_u32_e32 v223, vcc, 0, v223, vcc
	global_load_dwordx4 v[218:221], v[222:223], off offset:3072
	s_waitcnt vmcnt(17)
	v_pk_add_f32 v[70:71], v[70:71], v[228:229]
	v_pk_add_f32 v[68:69], v[68:69], v[226:227]
	v_add_co_u32_e32 v222, vcc, 0x1000, v222
	s_nop 1
	v_addc_co_u32_e32 v223, vcc, 0, v223, vcc
	global_load_dwordx4 v[226:229], v[222:223], off offset:3072
	s_waitcnt vmcnt(17)
	v_pk_add_f32 v[66:67], v[66:67], v[232:233]
	v_pk_add_f32 v[64:65], v[64:65], v[230:231]
	v_add_co_u32_e32 v222, vcc, 0x1d000, v222
	s_nop 1
	v_addc_co_u32_e32 v223, vcc, 0, v223, vcc
	global_load_dwordx4 v[230:233], v[222:223], off offset:3072
	s_waitcnt vmcnt(17)
	v_pk_add_f32 v[70:71], v[70:71], v[236:237]
	v_pk_add_f32 v[68:69], v[68:69], v[234:235]
	v_add_co_u32_e32 v222, vcc, 0x1000, v222
	s_nop 1
	v_addc_co_u32_e32 v223, vcc, 0, v223, vcc
	global_load_dwordx4 v[234:237], v[222:223], off offset:3072
	s_waitcnt vmcnt(17)
	v_pk_add_f32 v[66:67], v[66:67], v[240:241]
	v_pk_add_f32 v[64:65], v[64:65], v[238:239]
	v_add_co_u32_e32 v222, vcc, 0x1d000, v222
	s_nop 1
	v_addc_co_u32_e32 v223, vcc, 0, v223, vcc
	global_load_dwordx4 v[238:241], v[222:223], off offset:3072
	s_waitcnt vmcnt(17)
	v_pk_add_f32 v[70:71], v[70:71], v[244:245]
	v_pk_add_f32 v[68:69], v[68:69], v[242:243]
	v_add_co_u32_e32 v222, vcc, 0x1000, v222
	s_nop 1
	v_addc_co_u32_e32 v223, vcc, 0, v223, vcc
	global_load_dwordx4 v[242:245], v[222:223], off offset:3072
	s_waitcnt vmcnt(17)
	v_pk_add_f32 v[66:67], v[66:67], v[248:249]
	v_pk_add_f32 v[64:65], v[64:65], v[246:247]
	v_add_co_u32_e32 v222, vcc, 0x1d000, v222
	s_nop 1
	v_addc_co_u32_e32 v223, vcc, 0, v223, vcc
	global_load_dwordx4 v[246:249], v[222:223], off offset:3072
	s_waitcnt vmcnt(17)
	v_pk_add_f32 v[70:71], v[70:71], v[252:253]
	v_pk_add_f32 v[68:69], v[68:69], v[250:251]
	v_add_co_u32_e32 v222, vcc, 0x1000, v222
	s_nop 1
	v_addc_co_u32_e32 v223, vcc, 0, v223, vcc
	global_load_dwordx4 v[250:253], v[222:223], off offset:3072
	s_waitcnt vmcnt(15)
	v_pk_add_f32 v[90:91], v[90:91], v[188:189]
	v_pk_add_f32 v[88:89], v[88:89], v[186:187]
	s_waitcnt vmcnt(14)
	v_pk_add_f32 v[94:95], v[94:95], v[192:193]
	v_pk_add_f32 v[92:93], v[92:93], v[190:191]
	s_waitcnt vmcnt(13)
	v_pk_add_f32 v[90:91], v[90:91], v[196:197]
	v_pk_add_f32 v[88:89], v[88:89], v[194:195]
	s_waitcnt vmcnt(12)
	v_pk_add_f32 v[94:95], v[94:95], v[200:201]
	v_pk_add_f32 v[92:93], v[92:93], v[198:199]
	s_waitcnt vmcnt(11)
	v_pk_add_f32 v[90:91], v[90:91], v[204:205]
	v_pk_add_f32 v[88:89], v[88:89], v[202:203]
	s_waitcnt vmcnt(10)
	v_pk_add_f32 v[94:95], v[94:95], v[208:209]
	v_pk_add_f32 v[92:93], v[92:93], v[206:207]
	s_waitcnt vmcnt(9)
	v_pk_add_f32 v[90:91], v[90:91], v[212:213]
	v_pk_add_f32 v[88:89], v[88:89], v[210:211]
	s_waitcnt vmcnt(8)
	v_pk_add_f32 v[94:95], v[94:95], v[216:217]
	v_pk_add_f32 v[92:93], v[92:93], v[214:215]
	s_waitcnt vmcnt(7)
	v_pk_add_f32 v[90:91], v[90:91], v[220:221]
	v_pk_add_f32 v[88:89], v[88:89], v[218:219]
	s_waitcnt vmcnt(6)
	v_pk_add_f32 v[94:95], v[94:95], v[228:229]
	v_pk_add_f32 v[92:93], v[92:93], v[226:227]
	s_waitcnt vmcnt(5)
	v_pk_add_f32 v[90:91], v[90:91], v[232:233]
	v_pk_add_f32 v[88:89], v[88:89], v[230:231]
	s_waitcnt vmcnt(4)
	v_pk_add_f32 v[94:95], v[94:95], v[236:237]
	v_pk_add_f32 v[92:93], v[92:93], v[234:235]
	s_waitcnt vmcnt(3)
	v_pk_add_f32 v[90:91], v[90:91], v[240:241]
	v_pk_add_f32 v[88:89], v[88:89], v[238:239]
	s_waitcnt vmcnt(2)
	v_pk_add_f32 v[94:95], v[94:95], v[244:245]
	v_pk_add_f32 v[92:93], v[92:93], v[242:243]
	s_waitcnt vmcnt(1)
	v_pk_add_f32 v[90:91], v[90:91], v[248:249]
	v_pk_add_f32 v[88:89], v[88:89], v[246:247]
	s_waitcnt vmcnt(0)
	v_pk_add_f32 v[94:95], v[94:95], v[252:253]
	v_pk_add_f32 v[92:93], v[92:93], v[250:251]
	v_mov_b32_e32 v185, v145
.Lnm0_early_skip:
	s_or_b64 exec, exec, s[6:7]
	v_min_i32_e32 v24, v144, v177
	v_add_u32_e32 v26, 0xffffe000, v24
	v_ashrrev_i32_e32 v25, 31, v24
	v_cmp_gt_i32_e32 vcc, s12, v24
	v_mov_b32_e32 v28, s39
	v_mov_b32_e32 v29, s37
	v_cndmask_b32_e32 v25, 0, v25, vcc
	v_cndmask_b32_e32 v24, v26, v24, vcc
	v_mov_b32_e32 v30, s38
	v_mov_b32_e32 v31, s36
	v_cndmask_b32_e32 v27, v28, v29, vcc
	v_cndmask_b32_e32 v26, v30, v31, vcc
	v_lshlrev_b64 v[24:25], 12, v[24:25]
	v_lshl_add_u64 v[24:25], v[26:27], 0, v[24:25]
	v_lshl_add_u64 v[24:25], v[24:25], 0, v[146:147]
	v_add_u32_e32 v170, 1, v144
	global_load_dwordx4 v[140:143], v[24:25], off nt
	global_load_dwordx4 v[136:139], v[24:25], off offset:1024 nt
	global_load_dwordx4 v[132:135], v[24:25], off offset:2048 nt
	global_load_dwordx4 v[128:131], v[24:25], off offset:3072 nt
	v_min_i32_e32 v24, v170, v177
	v_ashrrev_i32_e32 v25, 31, v24
	v_add_u32_e32 v26, 0xffffe000, v24
	v_cmp_gt_i32_e32 vcc, s12, v24
	v_add_u32_e32 v168, 2, v144
	v_add_u32_e32 v166, 3, v144
	v_cndmask_b32_e32 v25, 0, v25, vcc
	v_cndmask_b32_e32 v24, v26, v24, vcc
	v_cndmask_b32_e32 v27, v28, v29, vcc
	v_cndmask_b32_e32 v26, v30, v31, vcc
	v_lshlrev_b64 v[24:25], 12, v[24:25]
	v_lshl_add_u64 v[24:25], v[26:27], 0, v[24:25]
	v_lshl_add_u64 v[24:25], v[24:25], 0, v[146:147]
	global_load_dwordx4 v[124:127], v[24:25], off nt
	global_load_dwordx4 v[120:123], v[24:25], off offset:1024 nt
	global_load_dwordx4 v[116:119], v[24:25], off offset:2048 nt
	global_load_dwordx4 v[112:115], v[24:25], off offset:3072 nt
	v_min_i32_e32 v24, v168, v177
	v_ashrrev_i32_e32 v25, 31, v24
	v_add_u32_e32 v26, 0xffffe000, v24
	v_cmp_gt_i32_e32 vcc, s12, v24
	v_add_u32_e32 v164, 4, v144
	v_add_u32_e32 v162, 5, v144
	v_cndmask_b32_e32 v25, 0, v25, vcc
	v_cndmask_b32_e32 v24, v26, v24, vcc
	v_cndmask_b32_e32 v27, v28, v29, vcc
	v_cndmask_b32_e32 v26, v30, v31, vcc
	v_lshlrev_b64 v[24:25], 12, v[24:25]
	v_lshl_add_u64 v[24:25], v[26:27], 0, v[24:25]
	v_lshl_add_u64 v[24:25], v[24:25], 0, v[146:147]
	global_load_dwordx4 v[108:111], v[24:25], off nt
	global_load_dwordx4 v[104:107], v[24:25], off offset:1024 nt
	global_load_dwordx4 v[100:103], v[24:25], off offset:2048 nt
	global_load_dwordx4 v[96:99], v[24:25], off offset:3072 nt
	v_min_i32_e32 v24, v166, v177
	v_ashrrev_i32_e32 v25, 31, v24
	v_add_u32_e32 v26, 0xffffe000, v24
	v_cmp_gt_i32_e32 vcc, s12, v24
	v_add_u32_e32 v145, 0xffffe000, v144
	v_ashrrev_i32_e32 v145, 10, v145
	v_cndmask_b32_e32 v25, 0, v25, vcc
	v_cndmask_b32_e32 v24, v26, v24, vcc
	v_cndmask_b32_e32 v27, v28, v29, vcc
	v_cndmask_b32_e32 v26, v30, v31, vcc
	v_lshlrev_b64 v[24:25], 12, v[24:25]
	v_lshl_add_u64 v[24:25], v[26:27], 0, v[24:25]
	v_lshl_add_u64 v[24:25], v[24:25], 0, v[146:147]
	global_load_dwordx4 v[84:87], v[24:25], off nt
	global_load_dwordx4 v[80:83], v[24:25], off offset:1024 nt
	global_load_dwordx4 v[76:79], v[24:25], off offset:2048 nt
	global_load_dwordx4 v[72:75], v[24:25], off offset:3072 nt
	v_min_i32_e32 v24, v164, v177
	v_ashrrev_i32_e32 v25, 31, v24
	v_add_u32_e32 v26, 0xffffe000, v24
	v_cmp_gt_i32_e32 vcc, s12, v24
	v_add_u32_e32 v145, 1, v145
	s_nop 0
	v_cndmask_b32_e32 v25, 0, v25, vcc
	v_cndmask_b32_e32 v24, v26, v24, vcc
	v_cndmask_b32_e32 v27, v28, v29, vcc
	v_cndmask_b32_e32 v26, v30, v31, vcc
	v_lshlrev_b64 v[24:25], 12, v[24:25]
	v_lshl_add_u64 v[24:25], v[26:27], 0, v[24:25]
	v_min_i32_e32 v26, v162, v177
	v_ashrrev_i32_e32 v27, 31, v26
	v_add_u32_e32 v32, 0xffffe000, v26
	v_cmp_gt_i32_e32 vcc, s12, v26
	v_lshl_add_u64 v[24:25], v[24:25], 0, v[146:147]
	s_nop 0
	v_cndmask_b32_e32 v27, 0, v27, vcc
	v_cndmask_b32_e32 v26, v32, v26, vcc
	v_cndmask_b32_e32 v29, v28, v29, vcc
	v_cndmask_b32_e32 v28, v30, v31, vcc
	v_lshlrev_b64 v[26:27], 12, v[26:27]
	v_lshl_add_u64 v[26:27], v[28:29], 0, v[26:27]
	v_lshl_add_u64 v[26:27], v[26:27], 0, v[146:147]
	global_load_dwordx4 v[60:63], v[24:25], off nt
	global_load_dwordx4 v[56:59], v[24:25], off offset:1024 nt
	global_load_dwordx4 v[52:55], v[24:25], off offset:2048 nt
	global_load_dwordx4 v[48:51], v[24:25], off offset:3072 nt
	global_load_dwordx4 v[36:39], v[26:27], off nt
	global_load_dwordx4 v[32:35], v[26:27], off offset:1024 nt
	global_load_dwordx4 v[28:31], v[26:27], off offset:2048 nt
	s_nop 0
	global_load_dwordx4 v[24:27], v[26:27], off offset:3072 nt
	v_cmp_lt_i32_e32 vcc, s13, v144
	s_nop 1
	v_cndmask_b32_e32 v145, 0, v145, vcc
	v_cmp_ne_u32_e32 vcc, v145, v185
	s_and_saveexec_b64 s[6:7], vcc
	s_cbranch_execz .LBB0_111
